# rms_rows (bf16 output): gain vector preloaded once before the row loop, store phase no longer waits on each reload plus previous stores
# baseline (speedup 1.0000x reference)
; template <bool TO_BF16>
; __device__ __forceinline__ void rms_rows(const float* xp, const float* xs, const float* __restrict__ g, u16* h, float* yo) {
;     const int tid_ = opaque_tid(); const int wid = tid_ >> 6, lane = tid_ & 63;
;     const int stride = gridDim.x * 8;
;     for (int row0 = blockIdx.x * 8 + wid; row0 < M; row0 += 2 * stride) {
;         const int rowB = row0 + stride; const bool hasB = rowB < M;
;         const float* srcA = row0 < MP ? xp + (size_t)row0 * D : xs + (size_t)(row0 - MP) * D;
;         const float* srcB = hasB ? (rowB < MP ? xp + (size_t)rowB * D : xs + (size_t)(rowB - MP) * D) : srcA;
;         f32x4 va[8], vb[8]; float sa = 0.f, sb = 0.f;
; #pragma unroll
;         for (int i = 0; i < 8; ++i) { va[i] = *(const f32x4*)(srcA + i * 256 + lane * 4); vb[i] = *(const f32x4*)(srcB + i * 256 + lane * 4); }
; #pragma unroll
;         for (int i = 0; i < 8; ++i) { sa += va[i][0] * va[i][0] + va[i][1] * va[i][1] + va[i][2] * va[i][2] + va[i][3] * va[i][3];
;                                       sb += vb[i][0] * vb[i][0] + vb[i][1] * vb[i][1] + vb[i][2] * vb[i][2] + vb[i][3] * vb[i][3]; }
;         sa = wave_sum(sa); sb = wave_sum(sb);
;         const float ra = rsqrtf(sa * (1.0f / D) + 1e-6f), rb = rsqrtf(sb * (1.0f / D) + 1e-6f);
; #pragma unroll
;         for (int i = 0; i < 8; ++i) {
;             const f32x4 gg = *(const f32x4*)(g + i * 256 + lane * 4);
.LBB0_46:
	s_mov_b64 s[0:1], src_shared_base
	s_add_u32 s34, s74, 0x9f85000
	s_getreg_b32 s0, hwreg(HW_REG_HW_ID, 0, 6)
	s_addc_u32 s35, s75, 0
	s_and_b32 s0, s0, 63
	s_lshl_b32 s0, s0, 2
	s_add_i32 s0, s0, 0
	s_add_i32 s0, s0, 0x20100
	v_mov_b32_e32 v2, s0
	v_mov_b32_e32 v3, s1
	flat_load_dword v2, v[2:3] sc0 sc1
	s_waitcnt vmcnt(0)
	s_lshl_b32 s1, s92, 3
	s_movk_i32 s14, 0x4100
	v_writelane_b32 v252, s76, 37
	s_lshl_b32 s93, s33, 3
	v_writelane_b32 v252, s1, 38
	s_waitcnt lgkmcnt(0)
	v_readfirstlane_b32 s0, v2
	s_nop 1
	v_lshl_or_b32 v2, s0, 6, v214
	s_nop 0
	v_ashrrev_i32_e32 v3, 6, v2
	v_add_u32_e32 v88, s1, v3
	v_cmp_gt_i32_e32 vcc, s14, v88
	s_and_saveexec_b64 s[4:5], vcc
	s_cbranch_execz .LBB0_71
	v_lshlrev_b32_e32 v2, 2, v2
	v_and_b32_e32 v6, 0xfc, v2
	v_readlane_b32 s76, v252, 21
	v_lshlrev_b32_e32 v70, 2, v6
	v_readlane_b32 s90, v252, 35
	v_readlane_b32 s91, v252, 36
	v_mov_b32_e32 v71, 0
	s_mov_b64 s[0:1], 0x1000
	v_lshl_add_u64 v[72:73], s[90:91], 0, v[70:71]
	v_lshl_add_u64 v[76:77], v[72:73], 0, s[0:1]
	s_mov_b64 s[0:1], 0x1400
	global_load_dwordx4 v[2:5], v70, s[90:91]
	v_lshl_add_u64 v[78:79], v[72:73], 0, s[0:1]
	s_mov_b64 s[0:1], 0x1800
	v_readlane_b32 s77, v252, 22
	v_readlane_b32 s78, v252, 23
	v_readlane_b32 s79, v252, 24
	v_lshlrev_b32_e32 v8, 1, v6
	v_mov_b32_e32 v9, v71
	v_lshl_add_u64 v[80:81], v[72:73], 0, s[0:1]
	s_mov_b64 s[0:1], 0x1c00
	v_lshl_add_u64 v[74:75], s[34:35], 0, v[8:9]
	v_lshl_add_u64 v[82:83], v[72:73], 0, s[0:1]
	s_movk_i32 s15, 0x4000
	v_mov_b32_e32 v92, s79
	v_mov_b32_e32 v93, s77
	v_mov_b32_e32 v94, s78
	v_mov_b32_e32 v95, s76
	s_movk_i32 s16, 0x3fff
	v_lshlrev_b32_e32 v84, 2, v6
	v_mov_b32_e32 v85, v71
	s_movk_i32 s17, 0x1000
	v_mov_b32_e32 v96, 0x358637bd
	s_mov_b32 s18, 0x800000
	s_movk_i32 s19, 0x40ff
	v_mov_b32_e32 v97, 0x3a000000
	v_readlane_b32 s80, v252, 25
	v_readlane_b32 s81, v252, 26
	v_readlane_b32 s82, v252, 27
	v_readlane_b32 s83, v252, 28
	v_readlane_b32 s84, v252, 29
	v_readlane_b32 s85, v252, 30
	v_readlane_b32 s86, v252, 31
	v_readlane_b32 s87, v252, 32
	v_readlane_b32 s88, v252, 33
	v_readlane_b32 s89, v252, 34
	global_load_dwordx4 v[160:163], v[72:73], off offset:1024
	global_load_dwordx4 v[164:167], v[72:73], off offset:2048
	global_load_dwordx4 v[168:171], v[72:73], off offset:3072
	global_load_dwordx4 v[172:175], v[76:77], off
	global_load_dwordx4 v[176:179], v[78:79], off
	global_load_dwordx4 v[180:183], v[80:81], off
	global_load_dwordx4 v[184:187], v[82:83], off
	s_branch .LBB0_49

; __device__ __forceinline__ unsigned pk_bf16(float lo, float hi) { unsigned r; asm("v_cvt_pk_bf16_f32 %0, %1, %2" : "=v"(r) : "v"(lo), "v"(hi)); return r; }
; template <bool TO_BF16>
; __device__ __forceinline__ void rms_rows(const float* xp, const float* xs, const float* __restrict__ g, u16* h, float* yo) {
;     ...
; #pragma unroll
;         for (int i = 0; i < 8; ++i) {
;             const f32x4 gg = *(const f32x4*)(g + i * 256 + lane * 4);
;             f32x4 oa, ob;
; #pragma unroll
;             for (int e = 0; e < 4; ++e) { oa[e] = va[i][e] * ra * gg[e]; ob[e] = vb[i][e] * rb * gg[e]; }
;             if (TO_BF16) {
;                 u32x2 w; w.x = pk_bf16(oa[0], oa[1]); w.y = pk_bf16(oa[2], oa[3]); *(u32x2*)(h + (size_t)row0 * D + i * 256 + lane * 4) = w;
;                 if (hasB) { w.x = pk_bf16(ob[0], ob[1]); w.y = pk_bf16(ob[2], ob[3]); *(u32x2*)(h + (size_t)rowB * D + i * 256 + lane * 4) = w; }
.LBB0_57:
	s_or_b64 exec, exec, s[10:11]
	v_mul_f32_e32 v14, v14, v70
	v_mul_f32_e32 v15, v15, v70
	v_mul_f32_e32 v16, v16, v70
	v_mul_f32_e32 v17, v17, v70
	v_mul_f32_e32 v14, v14, v160
	v_mul_f32_e32 v15, v15, v161
	v_mul_f32_e32 v16, v16, v162
	v_mul_f32_e32 v17, v17, v163
	v_cvt_pk_bf16_f32 v14, v14, v15
	v_cvt_pk_bf16_f32 v15, v16, v17
	global_store_dwordx2 v[90:91], v[14:15], off offset:512
	s_and_saveexec_b64 s[10:11], s[0:1]
	s_cbranch_execz .LBB0_59
	v_mul_f32_e32 v14, v65, v98
	v_mul_f32_e32 v15, v14, v163
	v_mul_f32_e32 v14, v64, v98
	v_mul_f32_e32 v16, v14, v162
	v_mul_f32_e32 v14, v63, v98
	v_mul_f32_e32 v14, v14, v161
	v_mul_f32_e32 v17, v62, v98
	v_mul_f32_e32 v17, v17, v160
	v_cvt_pk_bf16_f32 v14, v17, v14
	v_cvt_pk_bf16_f32 v15, v16, v15
	global_store_dwordx2 v[88:89], v[14:15], off offset:512
.LBB0_59:
	s_or_b64 exec, exec, s[10:11]
	v_mul_f32_e32 v10, v10, v70
	v_mul_f32_e32 v11, v11, v70
	v_mul_f32_e32 v12, v12, v70
	v_mul_f32_e32 v13, v13, v70
	v_mul_f32_e32 v10, v10, v164
	v_mul_f32_e32 v11, v11, v165
	v_mul_f32_e32 v12, v12, v166
	v_mul_f32_e32 v13, v13, v167
	v_cvt_pk_bf16_f32 v10, v10, v11
	v_cvt_pk_bf16_f32 v11, v12, v13
	global_store_dwordx2 v[90:91], v[10:11], off offset:1024
	s_and_saveexec_b64 s[10:11], s[0:1]
	s_cbranch_execz .LBB0_61
	v_mul_f32_e32 v10, v61, v98
	v_mul_f32_e32 v11, v10, v167
	v_mul_f32_e32 v10, v60, v98
	v_mul_f32_e32 v12, v10, v166
	v_mul_f32_e32 v10, v59, v98
	v_mul_f32_e32 v10, v10, v165
	v_mul_f32_e32 v13, v58, v98
	v_mul_f32_e32 v13, v13, v164
	v_cvt_pk_bf16_f32 v10, v13, v10
	v_cvt_pk_bf16_f32 v11, v12, v11
	global_store_dwordx2 v[88:89], v[10:11], off offset:1024
.LBB0_61:
	s_or_b64 exec, exec, s[10:11]
	v_mul_f32_e32 v6, v6, v70
	v_mul_f32_e32 v7, v7, v70
	v_mul_f32_e32 v8, v8, v70
	v_mul_f32_e32 v9, v9, v70
	v_mul_f32_e32 v6, v6, v168
	v_mul_f32_e32 v7, v7, v169
	v_mul_f32_e32 v8, v8, v170
	v_mul_f32_e32 v9, v9, v171
	v_cvt_pk_bf16_f32 v6, v6, v7
	v_cvt_pk_bf16_f32 v7, v8, v9
	global_store_dwordx2 v[90:91], v[6:7], off offset:1536
	s_and_saveexec_b64 s[10:11], s[0:1]
	s_cbranch_execz .LBB0_63
	v_mul_f32_e32 v6, v57, v98
	v_mul_f32_e32 v7, v6, v171
	v_mul_f32_e32 v6, v56, v98
	v_mul_f32_e32 v8, v6, v170
	v_mul_f32_e32 v6, v55, v98
	v_mul_f32_e32 v6, v6, v169
	v_mul_f32_e32 v9, v54, v98
	v_mul_f32_e32 v9, v9, v168
	v_cvt_pk_bf16_f32 v6, v9, v6
	v_cvt_pk_bf16_f32 v7, v8, v7
	global_store_dwordx2 v[88:89], v[6:7], off offset:1536
.LBB0_63:
	s_or_b64 exec, exec, s[10:11]
	v_mul_f32_e32 v10, v50, v70
	v_mul_f32_e32 v11, v51, v70
	v_mul_f32_e32 v12, v52, v70
	v_mul_f32_e32 v13, v53, v70
	v_mul_f32_e32 v10, v10, v172
	v_mul_f32_e32 v11, v11, v173
	v_mul_f32_e32 v12, v12, v174
	v_mul_f32_e32 v13, v13, v175
	v_cvt_pk_bf16_f32 v10, v10, v11
	v_cvt_pk_bf16_f32 v11, v12, v13
	global_store_dwordx2 v[90:91], v[10:11], off offset:2048
	s_and_saveexec_b64 s[10:11], s[0:1]
	s_cbranch_execz .LBB0_65
	v_mul_f32_e32 v10, v49, v98
	v_mul_f32_e32 v9, v10, v175
	v_mul_f32_e32 v10, v48, v98
	v_mul_f32_e32 v8, v10, v174
	v_mul_f32_e32 v10, v47, v98
	v_mul_f32_e32 v7, v10, v173
	v_mul_f32_e32 v10, v46, v98
	v_mul_f32_e32 v6, v10, v172
	v_cvt_pk_bf16_f32 v6, v6, v7
	v_cvt_pk_bf16_f32 v7, v8, v9
	global_store_dwordx2 v[88:89], v[6:7], off offset:2048
.LBB0_65:
	s_or_b64 exec, exec, s[10:11]
	v_mul_f32_e32 v10, v42, v70
	v_mul_f32_e32 v11, v43, v70
	v_mul_f32_e32 v12, v44, v70
	v_mul_f32_e32 v13, v45, v70
	v_mul_f32_e32 v10, v10, v176
	v_mul_f32_e32 v11, v11, v177
	v_mul_f32_e32 v12, v12, v178
	v_mul_f32_e32 v13, v13, v179
	v_cvt_pk_bf16_f32 v10, v10, v11
	v_cvt_pk_bf16_f32 v11, v12, v13
	global_store_dwordx2 v[90:91], v[10:11], off offset:2560
	s_and_saveexec_b64 s[10:11], s[0:1]
	s_cbranch_execz .LBB0_67
	v_mul_f32_e32 v10, v41, v98
	v_mul_f32_e32 v9, v10, v179
	v_mul_f32_e32 v10, v40, v98
	v_mul_f32_e32 v8, v10, v178
	v_mul_f32_e32 v10, v39, v98
	v_mul_f32_e32 v7, v10, v177
	v_mul_f32_e32 v10, v38, v98
	v_mul_f32_e32 v6, v10, v176
	v_cvt_pk_bf16_f32 v6, v6, v7
	v_cvt_pk_bf16_f32 v7, v8, v9
	global_store_dwordx2 v[88:89], v[6:7], off offset:2560
.LBB0_67:
	s_or_b64 exec, exec, s[10:11]
	v_mul_f32_e32 v10, v30, v70
	v_mul_f32_e32 v11, v31, v70
	v_mul_f32_e32 v12, v32, v70
	v_mul_f32_e32 v13, v33, v70
	v_mul_f32_e32 v10, v10, v180
	v_mul_f32_e32 v11, v11, v181
	v_mul_f32_e32 v12, v12, v182
	v_mul_f32_e32 v13, v13, v183
	v_cvt_pk_bf16_f32 v10, v10, v11
	v_cvt_pk_bf16_f32 v11, v12, v13
	global_store_dwordx2 v[90:91], v[10:11], off offset:3072
	s_and_saveexec_b64 s[10:11], s[0:1]
	s_cbranch_execz .LBB0_69
	v_mul_f32_e32 v10, v37, v98
	v_mul_f32_e32 v9, v10, v183
	v_mul_f32_e32 v10, v36, v98
	v_mul_f32_e32 v8, v10, v182
	v_mul_f32_e32 v10, v35, v98
	v_mul_f32_e32 v7, v10, v181
	v_mul_f32_e32 v10, v34, v98
	v_mul_f32_e32 v6, v10, v180
	v_cvt_pk_bf16_f32 v6, v6, v7
	v_cvt_pk_bf16_f32 v7, v8, v9
	global_store_dwordx2 v[88:89], v[6:7], off offset:3072
.LBB0_69:
	s_or_b64 exec, exec, s[10:11]
	v_mul_f32_e32 v10, v18, v70
	v_mul_f32_e32 v11, v19, v70
	v_mul_f32_e32 v12, v20, v70
	v_mul_f32_e32 v13, v21, v70
	v_mul_f32_e32 v10, v10, v184
	v_mul_f32_e32 v11, v11, v185
	v_mul_f32_e32 v12, v12, v186
	v_mul_f32_e32 v13, v13, v187
	v_cvt_pk_bf16_f32 v10, v10, v11
	v_cvt_pk_bf16_f32 v11, v12, v13
	global_store_dwordx2 v[90:91], v[10:11], off offset:3584
	s_and_saveexec_b64 s[10:11], s[0:1]
	s_cbranch_execz .LBB0_48
	v_mul_f32_e32 v10, v25, v98
	v_mul_f32_e32 v9, v10, v187
	v_mul_f32_e32 v10, v24, v98
	v_mul_f32_e32 v8, v10, v186
	v_mul_f32_e32 v10, v23, v98
	v_mul_f32_e32 v7, v10, v185
	v_mul_f32_e32 v10, v22, v98
	v_mul_f32_e32 v6, v10, v184
	v_cvt_pk_bf16_f32 v6, v6, v7
	v_cvt_pk_bf16_f32 v7, v8, v9
	global_store_dwordx2 v[88:89], v[6:7], off offset:3584
	s_branch .LBB0_48

; template <bool TO_BF16>
; __device__ __forceinline__ void rms_rows(const float* xp, const float* xs, const float* __restrict__ g, u16* h, float* yo) {
;     const int tid_ = opaque_tid(); const int wid = tid_ >> 6, lane = tid_ & 63;
;     const int stride = gridDim.x * 8;
;     for (int row0 = blockIdx.x * 8 + wid; row0 < M; row0 += 2 * stride) {
;         const int rowB = row0 + stride; const bool hasB = rowB < M;
;         const float* srcA = row0 < MP ? xp + (size_t)row0 * D : xs + (size_t)(row0 - MP) * D;
;         const float* srcB = hasB ? (rowB < MP ? xp + (size_t)rowB * D : xs + (size_t)(rowB - MP) * D) : srcA;
;         f32x4 va[8], vb[8]; float sa = 0.f, sb = 0.f;
; #pragma unroll
;         for (int i = 0; i < 8; ++i) { va[i] = *(const f32x4*)(srcA + i * 256 + lane * 4); vb[i] = *(const f32x4*)(srcB + i * 256 + lane * 4); }
; #pragma unroll
;         for (int i = 0; i < 8; ++i) { sa += va[i][0] * va[i][0] + va[i][1] * va[i][1] + va[i][2] * va[i][2] + va[i][3] * va[i][3];
;                                       sb += vb[i][0] * vb[i][0] + vb[i][1] * vb[i][1] + vb[i][2] * vb[i][2] + vb[i][3] * vb[i][3]; }
;         sa = wave_sum(sa); sb = wave_sum(sb);
;         const float ra = rsqrtf(sa * (1.0f / D) + 1e-6f), rb = rsqrtf(sb * (1.0f / D) + 1e-6f);
; #pragma unroll
;         for (int i = 0; i < 8; ++i) {
;             const f32x4 gg = *(const f32x4*)(g + i * 256 + lane * 4);
.LBB0_2315:
	s_or_b64 exec, exec, s[6:7]
	s_mov_b64 s[0:1], src_shared_base
	s_waitcnt lgkmcnt(0)
	s_barrier
	s_add_u32 s16, s72, 0x8000000
	s_getreg_b32 s0, hwreg(HW_REG_HW_ID, 0, 6)
	s_addc_u32 s17, s73, 0
	s_and_b32 s0, s0, 63
	s_lshl_b32 s0, s0, 2
	s_add_i32 s0, s0, 0
	s_add_i32 s0, s0, 0x20100
	v_mov_b32_e32 v0, s0
	v_mov_b32_e32 v1, s1
	flat_load_dword v0, v[0:1] sc0 sc1
	s_waitcnt vmcnt(0) lgkmcnt(0)
	v_readfirstlane_b32 s0, v0
	s_nop 1
	v_lshl_or_b32 v0, s0, 6, v214
	v_readlane_b32 s0, v252, 38
	v_ashrrev_i32_e32 v1, 6, v0
	s_nop 0
	v_add_u32_e32 v86, s0, v1
	s_movk_i32 s0, 0x4100
	v_cmp_gt_i32_e32 vcc, s0, v86
	s_and_saveexec_b64 s[10:11], vcc
	s_cbranch_execz .LBB0_2340
	v_lshlrev_b32_e32 v0, 2, v0
	v_and_b32_e32 v4, 0xfc, v0
	v_readlane_b32 s36, v252, 21
	v_mov_b32_e32 v69, 0
	v_lshlrev_b32_e32 v68, 2, v4
	v_readlane_b32 s50, v252, 35
	v_readlane_b32 s51, v252, 36
	s_mov_b64 s[2:3], 0x2000
	s_mov_b64 s[18:19], 0
	v_lshl_add_u64 v[6:7], s[50:51], 0, v[68:69]
	v_add_co_u32_e32 v0, vcc, 0x2000, v6
	v_lshl_add_u64 v[70:71], v[6:7], 0, s[2:3]
	s_nop 0
	v_addc_co_u32_e32 v1, vcc, 0, v7, vcc
	global_load_dwordx4 v[0:3], v[0:1], off
	s_mov_b64 s[2:3], 0x3000
	v_lshl_add_u64 v[74:75], v[6:7], 0, s[2:3]
	s_mov_b64 s[2:3], 0x3400
	v_lshl_add_u64 v[76:77], v[6:7], 0, s[2:3]
	s_mov_b64 s[2:3], 0x3800
	v_lshlrev_b32_e32 v68, 1, v4
	v_lshl_add_u64 v[78:79], v[6:7], 0, s[2:3]
	s_mov_b64 s[2:3], 0x3c00
	v_lshl_add_u64 v[72:73], s[34:35], 0, v[68:69]
	v_lshl_add_u64 v[80:81], v[6:7], 0, s[2:3]
	s_movk_i32 s1, 0x4000
	v_mov_b32_e32 v90, s17
	v_mov_b32_e32 v91, s73
	v_mov_b32_e32 v92, s16
	v_mov_b32_e32 v93, s72
	s_movk_i32 s2, 0x3fff
	v_lshlrev_b32_e32 v82, 2, v4
	v_mov_b32_e32 v83, v69
	s_movk_i32 s3, 0x1000
	v_mov_b32_e32 v94, 0x358637bd
	s_mov_b32 s4, 0x800000
	s_movk_i32 s5, 0x40ff
	v_mov_b32_e32 v95, 0x3a000000
	v_readlane_b32 s37, v252, 22
	v_readlane_b32 s38, v252, 23
	v_readlane_b32 s39, v252, 24
	v_readlane_b32 s40, v252, 25
	v_readlane_b32 s41, v252, 26
	v_readlane_b32 s42, v252, 27
	v_readlane_b32 s43, v252, 28
	v_readlane_b32 s44, v252, 29
	v_readlane_b32 s45, v252, 30
	v_readlane_b32 s46, v252, 31
	v_readlane_b32 s47, v252, 32
	v_readlane_b32 s48, v252, 33
	v_readlane_b32 s49, v252, 34
	global_load_dwordx4 v[160:163], v[70:71], off offset:1024
	global_load_dwordx4 v[164:167], v[70:71], off offset:2048
	global_load_dwordx4 v[168:171], v[70:71], off offset:3072
	global_load_dwordx4 v[172:175], v[74:75], off
	global_load_dwordx4 v[176:179], v[76:77], off
	global_load_dwordx4 v[180:183], v[78:79], off
	global_load_dwordx4 v[184:187], v[80:81], off
	s_branch .LBB0_2318

; __device__ __forceinline__ unsigned pk_bf16(float lo, float hi) { unsigned r; asm("v_cvt_pk_bf16_f32 %0, %1, %2" : "=v"(r) : "v"(lo), "v"(hi)); return r; }
; template <bool TO_BF16>
; __device__ __forceinline__ void rms_rows(const float* xp, const float* xs, const float* __restrict__ g, u16* h, float* yo) {
;     ...
; #pragma unroll
;         for (int i = 0; i < 8; ++i) {
;             const f32x4 gg = *(const f32x4*)(g + i * 256 + lane * 4);
;             f32x4 oa, ob;
; #pragma unroll
;             for (int e = 0; e < 4; ++e) { oa[e] = va[i][e] * ra * gg[e]; ob[e] = vb[i][e] * rb * gg[e]; }
;             if (TO_BF16) {
;                 u32x2 w; w.x = pk_bf16(oa[0], oa[1]); w.y = pk_bf16(oa[2], oa[3]); *(u32x2*)(h + (size_t)row0 * D + i * 256 + lane * 4) = w;
;                 if (hasB) { w.x = pk_bf16(ob[0], ob[1]); w.y = pk_bf16(ob[2], ob[3]); *(u32x2*)(h + (size_t)rowB * D + i * 256 + lane * 4) = w; }
.LBB0_2326:
	s_or_b64 exec, exec, s[8:9]
	v_mul_f32_e32 v56, v56, v96
	v_mul_f32_e32 v57, v57, v96
	v_mul_f32_e32 v58, v58, v96
	v_mul_f32_e32 v59, v59, v96
	v_mul_f32_e32 v56, v56, v160
	v_mul_f32_e32 v57, v57, v161
	v_mul_f32_e32 v58, v58, v162
	v_mul_f32_e32 v59, v59, v163
	v_cvt_pk_bf16_f32 v56, v56, v57
	v_cvt_pk_bf16_f32 v57, v58, v59
	global_store_dwordx2 v[88:89], v[56:57], off offset:512
	s_and_saveexec_b64 s[8:9], s[6:7]
	s_cbranch_execz .LBB0_2328
	v_mul_f32_e32 v53, v53, v68
	v_mul_f32_e32 v52, v52, v68
	v_mul_f32_e32 v55, v55, v68
	v_mul_f32_e32 v54, v54, v68
	v_mul_f32_e32 v53, v53, v161
	v_mul_f32_e32 v52, v52, v160
	v_mul_f32_e32 v55, v55, v163
	v_mul_f32_e32 v54, v54, v162
	v_cvt_pk_bf16_f32 v52, v52, v53
	v_cvt_pk_bf16_f32 v53, v54, v55
	global_store_dwordx2 v[86:87], v[52:53], off offset:512
.LBB0_2328:
	s_or_b64 exec, exec, s[8:9]
	v_mul_f32_e32 v48, v48, v96
	v_mul_f32_e32 v49, v49, v96
	v_mul_f32_e32 v50, v50, v96
	v_mul_f32_e32 v51, v51, v96
	v_mul_f32_e32 v48, v48, v164
	v_mul_f32_e32 v49, v49, v165
	v_mul_f32_e32 v50, v50, v166
	v_mul_f32_e32 v51, v51, v167
	v_cvt_pk_bf16_f32 v48, v48, v49
	v_cvt_pk_bf16_f32 v49, v50, v51
	global_store_dwordx2 v[88:89], v[48:49], off offset:1024
	s_and_saveexec_b64 s[8:9], s[6:7]
	s_cbranch_execz .LBB0_2330
	v_mul_f32_e32 v45, v45, v68
	v_mul_f32_e32 v44, v44, v68
	v_mul_f32_e32 v47, v47, v68
	v_mul_f32_e32 v46, v46, v68
	v_mul_f32_e32 v45, v45, v165
	v_mul_f32_e32 v44, v44, v164
	v_mul_f32_e32 v47, v47, v167
	v_mul_f32_e32 v46, v46, v166
	v_cvt_pk_bf16_f32 v44, v44, v45
	v_cvt_pk_bf16_f32 v45, v46, v47
	global_store_dwordx2 v[86:87], v[44:45], off offset:1024
.LBB0_2330:
	s_or_b64 exec, exec, s[8:9]
	v_mul_f32_e32 v40, v40, v96
	v_mul_f32_e32 v41, v41, v96
	v_mul_f32_e32 v42, v42, v96
	v_mul_f32_e32 v43, v43, v96
	v_mul_f32_e32 v40, v40, v168
	v_mul_f32_e32 v41, v41, v169
	v_mul_f32_e32 v42, v42, v170
	v_mul_f32_e32 v43, v43, v171
	v_cvt_pk_bf16_f32 v40, v40, v41
	v_cvt_pk_bf16_f32 v41, v42, v43
	global_store_dwordx2 v[88:89], v[40:41], off offset:1536
	s_and_saveexec_b64 s[8:9], s[6:7]
	s_cbranch_execz .LBB0_2332
	v_mul_f32_e32 v37, v37, v68
	v_mul_f32_e32 v36, v36, v68
	v_mul_f32_e32 v39, v39, v68
	v_mul_f32_e32 v38, v38, v68
	v_mul_f32_e32 v37, v37, v169
	v_mul_f32_e32 v36, v36, v168
	v_mul_f32_e32 v39, v39, v171
	v_mul_f32_e32 v38, v38, v170
	v_cvt_pk_bf16_f32 v36, v36, v37
	v_cvt_pk_bf16_f32 v37, v38, v39
	global_store_dwordx2 v[86:87], v[36:37], off offset:1536
.LBB0_2332:
	s_or_b64 exec, exec, s[8:9]
	v_mul_f32_e32 v32, v32, v96
	v_mul_f32_e32 v33, v33, v96
	v_mul_f32_e32 v34, v34, v96
	v_mul_f32_e32 v35, v35, v96
	v_mul_f32_e32 v32, v32, v172
	v_mul_f32_e32 v33, v33, v173
	v_mul_f32_e32 v34, v34, v174
	v_mul_f32_e32 v35, v35, v175
	v_cvt_pk_bf16_f32 v32, v32, v33
	v_cvt_pk_bf16_f32 v33, v34, v35
	global_store_dwordx2 v[88:89], v[32:33], off offset:2048
	s_and_saveexec_b64 s[8:9], s[6:7]
	s_cbranch_execz .LBB0_2334
	v_mul_f32_e32 v29, v29, v68
	v_mul_f32_e32 v28, v28, v68
	v_mul_f32_e32 v31, v31, v68
	v_mul_f32_e32 v30, v30, v68
	v_mul_f32_e32 v29, v29, v173
	v_mul_f32_e32 v28, v28, v172
	v_mul_f32_e32 v31, v31, v175
	v_mul_f32_e32 v30, v30, v174
	v_cvt_pk_bf16_f32 v28, v28, v29
	v_cvt_pk_bf16_f32 v29, v30, v31
	global_store_dwordx2 v[86:87], v[28:29], off offset:2048
.LBB0_2334:
	s_or_b64 exec, exec, s[8:9]
	v_mul_f32_e32 v24, v24, v96
	v_mul_f32_e32 v25, v25, v96
	v_mul_f32_e32 v26, v26, v96
	v_mul_f32_e32 v27, v27, v96
	v_mul_f32_e32 v24, v24, v176
	v_mul_f32_e32 v25, v25, v177
	v_mul_f32_e32 v26, v26, v178
	v_mul_f32_e32 v27, v27, v179
	v_cvt_pk_bf16_f32 v24, v24, v25
	v_cvt_pk_bf16_f32 v25, v26, v27
	global_store_dwordx2 v[88:89], v[24:25], off offset:2560
	s_and_saveexec_b64 s[8:9], s[6:7]
	s_cbranch_execz .LBB0_2336
	v_mul_f32_e32 v21, v21, v68
	v_mul_f32_e32 v20, v20, v68
	v_mul_f32_e32 v23, v23, v68
	v_mul_f32_e32 v22, v22, v68
	v_mul_f32_e32 v21, v21, v177
	v_mul_f32_e32 v20, v20, v176
	v_mul_f32_e32 v23, v23, v179
	v_mul_f32_e32 v22, v22, v178
	v_cvt_pk_bf16_f32 v20, v20, v21
	v_cvt_pk_bf16_f32 v21, v22, v23
	global_store_dwordx2 v[86:87], v[20:21], off offset:2560
.LBB0_2336:
	s_or_b64 exec, exec, s[8:9]
	v_mul_f32_e32 v16, v16, v96
	v_mul_f32_e32 v17, v17, v96
	v_mul_f32_e32 v18, v18, v96
	v_mul_f32_e32 v19, v19, v96
	v_mul_f32_e32 v16, v16, v180
	v_mul_f32_e32 v17, v17, v181
	v_mul_f32_e32 v18, v18, v182
	v_mul_f32_e32 v19, v19, v183
	v_cvt_pk_bf16_f32 v16, v16, v17
	v_cvt_pk_bf16_f32 v17, v18, v19
	global_store_dwordx2 v[88:89], v[16:17], off offset:3072
	s_and_saveexec_b64 s[8:9], s[6:7]
	s_cbranch_execz .LBB0_2338
	v_mul_f32_e32 v13, v13, v68
	v_mul_f32_e32 v12, v12, v68
	v_mul_f32_e32 v15, v15, v68
	v_mul_f32_e32 v14, v14, v68
	v_mul_f32_e32 v13, v13, v181
	v_mul_f32_e32 v12, v12, v180
	v_mul_f32_e32 v15, v15, v183
	v_mul_f32_e32 v14, v14, v182
	v_cvt_pk_bf16_f32 v12, v12, v13
	v_cvt_pk_bf16_f32 v13, v14, v15
	global_store_dwordx2 v[86:87], v[12:13], off offset:3072
.LBB0_2338:
	s_or_b64 exec, exec, s[8:9]
	v_mul_f32_e32 v8, v8, v96
	v_mul_f32_e32 v9, v9, v96
	v_mul_f32_e32 v10, v10, v96
	v_mul_f32_e32 v11, v11, v96
	v_mul_f32_e32 v8, v8, v184
	v_mul_f32_e32 v9, v9, v185
	v_mul_f32_e32 v10, v10, v186
	v_mul_f32_e32 v11, v11, v187
	v_cvt_pk_bf16_f32 v8, v8, v9
	v_cvt_pk_bf16_f32 v9, v10, v11
	global_store_dwordx2 v[88:89], v[8:9], off offset:3584
	s_and_saveexec_b64 s[8:9], s[6:7]
	s_cbranch_execz .LBB0_2317
	v_mul_f32_e32 v5, v5, v68
	v_mul_f32_e32 v4, v4, v68
	v_mul_f32_e32 v7, v7, v68
	v_mul_f32_e32 v6, v6, v68
	v_mul_f32_e32 v5, v5, v185
	v_mul_f32_e32 v4, v4, v184
	v_mul_f32_e32 v7, v7, v187
	v_mul_f32_e32 v6, v6, v186
	v_cvt_pk_bf16_f32 v4, v4, v5
	v_cvt_pk_bf16_f32 v5, v6, v7
	global_store_dwordx2 v[86:87], v[4:5], off offset:3584
	s_branch .LBB0_2317
